# sample attention loop: per-iteration s_setprio pair around the QK MFMA chain removed
# baseline (speedup 1.0000x reference)
.Lsa_noq:
	v_add3_u32 v160, s22, v144, v145
	v_add3_u32 v161, s22, v146, v147
	s_waitcnt lgkmcnt(0)
	v_mfma_f32_32x32x16_bf16 v[32:47], v[190:193], v[84:87], v[120:135]
	v_mfma_f32_32x32x16_bf16 v[48:63], v[214:217], v[84:87], v[120:135]
	s_waitcnt vmcnt(4)
	ds_write_b128 v160, v[96:99]
	v_add3_u32 v160, s22, v148, v149
	v_mfma_f32_32x32x16_bf16 v[32:47], v[194:197], v[80:83], v[32:47]
	v_mfma_f32_32x32x16_bf16 v[48:63], v[218:221], v[80:83], v[48:63]
	s_waitcnt vmcnt(3)
	ds_write_b128 v161, v[100:103]
	v_add_u32_e32 v161, s23, v150
	v_mfma_f32_32x32x16_bf16 v[32:47], v[198:201], v[76:79], v[32:47]
	v_mfma_f32_32x32x16_bf16 v[48:63], v[222:225], v[76:79], v[48:63]
	s_waitcnt vmcnt(2)
	ds_write_b128 v160, v[104:107]
	v_add_u32_e32 v160, v161, v152
	v_add_u32_e32 v161, v161, v153
	v_mfma_f32_32x32x16_bf16 v[32:47], v[202:205], v[72:75], v[32:47]
	v_mfma_f32_32x32x16_bf16 v[48:63], v[226:229], v[72:75], v[48:63]
	s_waitcnt vmcnt(1)
	ds_write_b128 v160, v[108:111] offset:26624
	s_waitcnt vmcnt(0)
	ds_write_b128 v161, v[112:115] offset:26624
	v_cndmask_b32_e64 v160, v238, v239, s[40:41]
	v_cndmask_b32_e64 v161, v238, v239, s[42:43]
	v_mfma_f32_32x32x16_bf16 v[32:47], v[206:209], v[68:71], v[32:47]
	v_mfma_f32_32x32x16_bf16 v[48:63], v[230:233], v[68:71], v[48:63]
	s_cmpk_gt_u32 s2, 0x46
	s_cbranch_scc1 .Lsa_nold
	global_load_dwordx4 v[96:99], v[240:241], off
	global_load_dwordx4 v[100:103], v[242:243], off
	global_load_dwordx4 v[104:107], v[244:245], off
	global_load_dwordx4 v[108:111], v[246:247], off
	global_load_dwordx4 v[112:115], v[248:249], off
.Lsa_nold:
	v_add_co_u32_e32 v240, vcc, v240, v160
	v_addc_co_u32_e32 v241, vcc, 0, v241, vcc
	v_add_co_u32_e32 v242, vcc, v242, v161
	v_addc_co_u32_e32 v243, vcc, 0, v243, vcc
	v_cndmask_b32_e64 v160, v238, v239, s[44:45]
	v_mfma_f32_32x32x16_bf16 v[32:47], v[210:213], v[64:67], v[32:47]
	v_mfma_f32_32x32x16_bf16 v[48:63], v[234:237], v[64:67], v[48:63]
	v_add_co_u32_e32 v244, vcc, v244, v160
	v_addc_co_u32_e32 v245, vcc, 0, v245, vcc
	v_add_co_u32_e32 v246, vcc, 0x80, v246
	v_addc_co_u32_e32 v247, vcc, 0, v247, vcc
	v_add_co_u32_e32 v248, vcc, 0x80, v248
	v_addc_co_u32_e32 v249, vcc, 0, v249, vcc
	s_nop 10
	v_max_f32_e32 v136, v48, v48
	v_max_f32_e32 v159, v32, v32
	v_max_f32_e32 v136, v159, v136
	v_max3_f32 v136, v136, v33, v49
	v_max3_f32 v136, v136, v34, v50
	v_max3_f32 v136, v136, v35, v51
	v_max3_f32 v136, v136, v36, v52
	v_max3_f32 v136, v136, v37, v53
	v_max3_f32 v136, v136, v38, v54
	v_max3_f32 v136, v136, v39, v55
	v_max3_f32 v136, v136, v40, v56
	v_max3_f32 v136, v136, v41, v57
	v_max3_f32 v136, v136, v42, v58
	v_max3_f32 v136, v136, v43, v59
	v_max3_f32 v136, v136, v44, v60
	v_max3_f32 v136, v136, v45, v61
	v_max3_f32 v136, v136, v46, v62
	v_max3_f32 v159, v136, v47, v63
	v_mov_b32_e32 v160, v159
	s_nop 1
	v_permlane32_swap_b32 v160, v159
	v_max_f32_e32 v159, v159, v160
	v_add_f32_e32 v160, v151, v120
	v_add_f32_e32 v160, 0x41000000, v160
	v_cmp_gt_f32_e32 vcc, v159, v160
	s_cbranch_vccz .LBB0_381
	v_sub_f32_e32 v159, v159, v120
	v_max_f32_e32 v159, v159, v159
	v_max_f32_e32 v160, v151, v151
	v_max_f32_e32 v159, v160, v159
	v_sub_f32_e32 v151, v151, v159
	v_exp_f32_e32 v160, v151
	v_mov_b32_e32 v151, v159
	v_add_f32_e32 v162, v120, v151
	v_pk_mul_f32 v[30:31], v[30:31], v[160:161] op_sel_hi:[1,0]
	v_pk_mul_f32 v[28:29], v[28:29], v[160:161] op_sel_hi:[1,0]
	v_pk_mul_f32 v[26:27], v[26:27], v[160:161] op_sel_hi:[1,0]
	v_pk_mul_f32 v[24:25], v[24:25], v[160:161] op_sel_hi:[1,0]
	v_pk_mul_f32 v[22:23], v[22:23], v[160:161] op_sel_hi:[1,0]
	v_pk_mul_f32 v[20:21], v[20:21], v[160:161] op_sel_hi:[1,0]
	v_pk_mul_f32 v[18:19], v[18:19], v[160:161] op_sel_hi:[1,0]
	v_pk_mul_f32 v[16:17], v[16:17], v[160:161] op_sel_hi:[1,0]
	v_pk_mul_f32 v[14:15], v[14:15], v[160:161] op_sel_hi:[1,0]
	v_pk_mul_f32 v[12:13], v[12:13], v[160:161] op_sel_hi:[1,0]
	v_pk_mul_f32 v[10:11], v[10:11], v[160:161] op_sel_hi:[1,0]
	v_pk_mul_f32 v[8:9], v[8:9], v[160:161] op_sel_hi:[1,0]
	v_pk_mul_f32 v[6:7], v[6:7], v[160:161] op_sel_hi:[1,0]
	v_pk_mul_f32 v[4:5], v[4:5], v[160:161] op_sel_hi:[1,0]
	v_pk_mul_f32 v[2:3], v[2:3], v[160:161] op_sel_hi:[1,0]
	v_pk_mul_f32 v[0:1], v[0:1], v[160:161] op_sel_hi:[1,0]
	v_mul_f32_e32 v119, v119, v160
	v_sub_f32_e32 v32, v32, v162
	v_sub_f32_e32 v33, v33, v162
	v_sub_f32_e32 v34, v34, v162
	v_sub_f32_e32 v35, v35, v162
	v_sub_f32_e32 v36, v36, v162
	v_sub_f32_e32 v37, v37, v162
	v_sub_f32_e32 v38, v38, v162
	v_sub_f32_e32 v39, v39, v162
	v_sub_f32_e32 v40, v40, v162
	v_sub_f32_e32 v41, v41, v162
	v_sub_f32_e32 v42, v42, v162
	v_sub_f32_e32 v43, v43, v162
	v_sub_f32_e32 v44, v44, v162
	v_sub_f32_e32 v45, v45, v162
	v_sub_f32_e32 v46, v46, v162
	v_sub_f32_e32 v47, v47, v162
	v_sub_f32_e32 v48, v48, v162
	v_sub_f32_e32 v49, v49, v162
	v_sub_f32_e32 v50, v50, v162
	v_sub_f32_e32 v51, v51, v162
	v_sub_f32_e32 v52, v52, v162
	v_sub_f32_e32 v53, v53, v162
	v_sub_f32_e32 v54, v54, v162
	v_sub_f32_e32 v55, v55, v162
	v_sub_f32_e32 v56, v56, v162
	v_sub_f32_e32 v57, v57, v162
	v_sub_f32_e32 v58, v58, v162
	v_sub_f32_e32 v59, v59, v162
	v_sub_f32_e32 v60, v60, v162
	v_sub_f32_e32 v61, v61, v162
	v_sub_f32_e32 v62, v62, v162
	v_sub_f32_e32 v63, v63, v162
	v_xor_b32_e32 v120, 0x80000000, v151
	v_mov_b32_e32 v121, v120
	v_mov_b32_e32 v122, v120
	v_mov_b32_e32 v123, v120
	v_mov_b32_e32 v124, v120
	v_mov_b32_e32 v125, v120
	v_mov_b32_e32 v126, v120
	v_mov_b32_e32 v127, v120
	v_mov_b32_e32 v128, v120
	v_mov_b32_e32 v129, v120
	v_mov_b32_e32 v130, v120
	v_mov_b32_e32 v131, v120
	v_mov_b32_e32 v132, v120
	v_mov_b32_e32 v133, v120
	v_mov_b32_e32 v134, v120
	v_mov_b32_e32 v135, v120
